# v040 + attention K/V tile loads through running 64-bit pointers (drops two v_mad_i64 + address adds per tile)
# baseline (speedup 1.0000x reference)
; #define LAS __attribute__((address_space(3)))
; #define A_LOAD(t) do { kreg0 = *(const u32x4*)(kg + (size_t)((t) * 64 + kv0) * 768 + kc0 * 8); if (tid < 256) kreg1 = *(const u32x4*)(kg + (size_t)((t) * 64 + kv1) * 768 + kc1 * 8); \
;         vreg = *(const u32x4*)(vg + (size_t)(t) * 64 * 512); } while (0)
; __device__ __forceinline__ void attn_unit(LAS unsigned char* lds, const bf16* Q, const bf16* Kp, const bf16* V, bf16* Y, int b, int h, int qb) {
;     ...
;     const int kv0 = tid / 12, kc0 = tid % 12, kv1 = (tid + 512) / 12, kc1 = (tid + 512) % 12;
;     const bf16* kg = Kp + rowbase * 768 + h * 96;
;     const bf16* vg = V + (rowbase + (tid & 63)) * 512 + h * 64 + 8 * (tid >> 6);
;     u32x4 kreg0, kreg1 = (u32x4){0, 0, 0, 0}, vreg;
;     ...
;     A_LOAD(0); A_STORE(0);
;     __syncthreads();
;     float m_run = 0.f, l_run = 0.f;
;     f32x16 o[2];
; #pragma unroll
;     for (int i = 0; i < 16; ++i) { o[0][i] = 0.f; o[1][i] = 0.f; }
;     const int qrel = wid * 32 + r32;
;     for (int t = 0; t < NT; ++t) {
;         const int buf = t & 1;
;         if (t + 1 < NT) A_LOAD(t + 1);
;         const int jb = t - (NT - 4);
;         const bool skip = (jb >= 0) && (64 * jb > wid * 32 + 31);
;         if (!skip) {
;             f32x16 p0, p1;
;             const float nm = -m_run;
; #pragma unroll
;             for (int i = 0; i < 16; ++i) { p0[i] = nm; p1[i] = nm; }
;             LAS const unsigned char* kb = lds + KOFF + buf * KBUF + r32 * KPB + hi * 16;
;             LAS const unsigned char* vb = lds + VOFF + buf * VBUF + r32 * VPB + hi * 8;
; #pragma unroll
;             for (int d0 = 0; d0 < 6; ++d0) p0 = __builtin_amdgcn_mfma_f32_32x32x16_bf16(*(LAS const bf16x8*)(kb + 32 * d0), qr[d0], p0, 0, 0, 0);
; #pragma unroll
;             for (int d0 = 0; d0 < 6; ++d0) p1 = __builtin_amdgcn_mfma_f32_32x32x16_bf16(*(LAS const bf16x8*)(kb + 32 * KPB + 32 * d0), qr[d0], p1, 0, 0, 0);
.LBB0_3632:
	s_or_b64 exec, exec, s[10:11]
	v_and_b32_e32 v11, 63, v4
	v_or_b32_e32 v4, s13, v11
	v_lshlrev_b32_e32 v4, 10, v4
	v_mov_b32_e32 v5, v64
	v_lshl_add_u64 v[4:5], s[64:65], 0, v[4:5]
	s_lshl_b32 s80, s9, 7
	v_lshl_add_u64 v[14:15], v[4:5], 0, s[80:81]
	v_lshlrev_b32_e32 v4, 3, v8
	v_ashrrev_i32_e32 v5, 31, v4
	v_lshl_add_u64 v[14:15], v[4:5], 1, v[14:15]
	flat_load_dwordx4 v[100:103], v[14:15]
	s_movk_i32 s10, 0xd0
	v_mul_lo_u32 v65, v9, s10
	v_lshlrev_b32_e32 v111, 4, v12
	v_add3_u32 v12, 0, v65, v111
	v_lshlrev_b32_e32 v113, 4, v13
	s_waitcnt vmcnt(0) lgkmcnt(0)
	ds_write_b128 v12, v[92:95]
	s_and_saveexec_b64 s[10:11], vcc
	s_xor_b64 s[10:11], exec, s[10:11]
	v_lshlrev_b32_e32 v113, 4, v13
	s_or_saveexec_b64 s[10:11], s[10:11]
	s_movk_i32 s13, 0xd0
	v_mul_lo_u32 v114, v10, s13
	s_xor_b64 exec, exec, s[10:11]
	v_add3_u32 v12, 0, v114, v113
	ds_write_b128 v12, v[96:99]
	s_or_b64 exec, exec, s[10:11]
	v_lshl_add_u64 v[66:67], v[0:1], 1, s[6:7]
	v_lshl_add_u64 v[106:107], v[2:3], 1, s[6:7]
	s_movk_i32 s6, 0xd0
	v_lshlrev_b32_e32 v12, 3, v6
	v_mad_u32_u24 v0, v7, s6, 0
	v_mul_i32_i24_e32 v1, 0xffffffb8, v7
	v_lshl_add_u32 v117, v6, 4, v0
	v_add3_u32 v118, v0, v1, v12
	v_mov_b32_e32 v0, s80
	v_mov_b32_e32 v1, v64
	v_lshlrev_b32_e32 v2, 10, v11
	s_movk_i32 s10, 0x440
	v_lshl_add_u64 v[0:1], v[4:5], 1, v[0:1]
	v_lshl_or_b32 v2, s23, 23, v2
	v_mov_b32_e32 v3, v64
	s_lshl_b32 s12, s12, 2
	v_mul_lo_u32 v8, v8, s10
	v_lshlrev_b32_e32 v13, 1, v11
	v_lshlrev_b32_e32 v112, 2, v6
	s_lshl_b32 s15, s22, 8
	v_lshl_add_u64 v[0:1], v[0:1], 0, v[2:3]
	v_mov_b32_e32 v123, 0
	s_lshl_b32 s9, s9, 6
	s_add_i32 s12, s12, 4
	s_mov_b32 s13, 1
	v_add3_u32 v115, 0, v8, v13
	v_or_b32_e32 v116, s14, v7
	s_or_b32 s14, s14, 31
	v_or_b32_e32 v119, s15, v112
	s_lshl_b32 s22, s22, 2
	v_add_u32_e32 v120, 64, v10
	v_add_u32_e32 v121, 64, v9
	v_lshl_add_u64 v[108:109], s[4:5], 0, v[0:1]
	s_mov_b32 s23, 0
	v_mov_b32_e32 v122, 0
	v_mov_b32_e32 v16, 0
	v_mov_b32_e32 v17, v123
	v_mov_b32_e32 v18, v123
	v_mov_b32_e32 v19, v123
	v_mov_b32_e32 v20, v123
	v_mov_b32_e32 v21, v123
	v_mov_b32_e32 v22, v123
	v_mov_b32_e32 v23, v123
	v_mov_b32_e32 v24, v123
	v_mov_b32_e32 v25, v123
	v_mov_b32_e32 v26, v123
	v_mov_b32_e32 v27, v123
	v_mov_b32_e32 v28, v123
	v_mov_b32_e32 v29, v123
	v_mov_b32_e32 v30, v123
	v_mov_b32_e32 v31, v123
	v_mov_b32_e32 v0, v123
	v_mov_b32_e32 v1, v123
	v_mov_b32_e32 v2, v123
	v_mov_b32_e32 v3, v123
	v_mov_b32_e32 v4, v123
	v_mov_b32_e32 v5, v123
	v_mov_b32_e32 v6, v123
	v_mov_b32_e32 v7, v123
	v_mov_b32_e32 v8, v123
	v_mov_b32_e32 v9, v123
	v_mov_b32_e32 v10, v123
	v_mov_b32_e32 v11, v123
	v_mov_b32_e32 v12, v123
	v_mov_b32_e32 v13, v123
	v_mov_b32_e32 v14, v123
	v_mov_b32_e32 v15, v123
	ds_write_b16 v115, v100 offset:26624
	ds_write_b16_d16_hi v115, v100 offset:26760
	ds_write_b16 v115, v101 offset:26896
	ds_write_b16_d16_hi v115, v101 offset:27032
	ds_write_b16 v115, v102 offset:27168
	ds_write_b16_d16_hi v115, v102 offset:27304
	ds_write_b16 v115, v103 offset:27440
	ds_write_b16_d16_hi v115, v103 offset:27576
	v_add_u32_e32 v32, s23, v121
	v_mad_i64_i32 v[32:33], s[10:11], v32, s87, v[66:67]
	global_load_dwordx4 v[142:145], v[32:33], off
	v_mov_b64_e32 v[34:35], v[32:33]
	s_and_saveexec_b64 s[10:11], s[38:39]
	v_add_u32_e32 v36, s23, v120
	v_mad_i64_i32 v[34:35], s[24:25], v36, s87, v[106:107]
	s_or_b64 exec, exec, s[10:11]
	global_load_dwordx4 v[146:149], v[34:35], off
	global_load_dwordx4 v[150:153], v[108:109], off
	s_mov_b64 s[6:7], 0x18000
	v_lshl_add_u64 v[154:155], v[32:33], 0, s[6:7]
	v_lshl_add_u64 v[156:157], v[34:35], 0, s[6:7]
	s_mov_b64 s[6:7], 0x10000
	v_lshl_add_u64 v[108:109], v[108:109], 0, s[6:7]
	s_movk_i32 s46, 0x3400
	s_movk_i32 s47, 0x2200
	s_waitcnt vmcnt(0)
	v_add3_u32 v110, s46, v65, v111
	ds_write_b128 v110, v[142:145]
	s_and_saveexec_b64 s[54:55], s[38:39]
	s_cbranch_execz .Lat_st2pre
	v_add3_u32 v110, s46, v114, v113
	ds_write_b128 v110, v[146:149]
.Lat_st2pre:
	s_or_b64 exec, exec, s[54:55]
	v_add_u32_e32 v110, s47, v115
	ds_write_b16 v110, v150 offset:26624
	ds_write_b16_d16_hi v110, v150 offset:26760
	ds_write_b16 v110, v151 offset:26896
	ds_write_b16_d16_hi v110, v151 offset:27032
	ds_write_b16 v110, v152 offset:27168
	ds_write_b16_d16_hi v110, v152 offset:27304
	ds_write_b16 v110, v153 offset:27440
	ds_write_b16_d16_hi v110, v153 offset:27576
	s_waitcnt lgkmcnt(0)
	global_load_dwordx4 v[142:145], v[154:155], off
	global_load_dwordx4 v[146:149], v[156:157], off
	global_load_dwordx4 v[150:153], v[108:109], off
	s_mov_b64 s[6:7], 0x18000
	v_lshl_add_u64 v[154:155], v[154:155], 0, s[6:7]
	v_lshl_add_u64 v[156:157], v[156:157], 0, s[6:7]
	s_mov_b64 s[6:7], 0x10000
	v_lshl_add_u64 v[108:109], v[108:109], 0, s[6:7]
	s_mov_b32 s44, 0
	s_mov_b32 s45, 0
	s_mov_b32 s48, 0xce00
	s_movk_i32 s49, 0x4400
	s_mov_b64 s[66:67], -1
	s_waitcnt lgkmcnt(0)
	s_barrier
	v_add_u32_e32 v110, s44, v117
	ds_read_b128 v[172:175], v110
	ds_read_b128 v[176:179], v110 offset:32
	ds_read_b128 v[180:183], v110 offset:64
	ds_read_b128 v[184:187], v110 offset:96
	ds_read_b128 v[188:191], v110 offset:128
	ds_read_b128 v[192:195], v110 offset:160
	ds_read_b128 v[198:201], v110 offset:6656
	ds_read_b128 v[202:205], v110 offset:6688
	ds_read_b128 v[206:209], v110 offset:6720
	ds_read_b128 v[222:225], v110 offset:6752
	ds_read_b128 v[226:229], v110 offset:6784
	ds_read_b128 v[230:233], v110 offset:6816
	s_branch .Lat_head
.Lat_head:
	s_add_i32 s25, s13, 2
	s_cmp_lt_u32 s25, s12
	s_cselect_b64 s[50:51], -1, 0
	s_cbranch_scc0 .Lat_noload_0
	global_load_dwordx4 v[92:95], v[154:155], off
	global_load_dwordx4 v[96:99], v[156:157], off
	global_load_dwordx4 v[100:103], v[108:109], off
	s_mov_b64 s[6:7], 0x18000
	v_lshl_add_u64 v[154:155], v[154:155], 0, s[6:7]
	v_lshl_add_u64 v[156:157], v[156:157], 0, s[6:7]

; #define A_LOAD(t) do { kreg0 = *(const u32x4*)(kg + (size_t)((t) * 64 + kv0) * 768 + kc0 * 8); if (tid < 256) kreg1 = *(const u32x4*)(kg + (size_t)((t) * 64 + kv1) * 768 + kc1 * 8); \
;         vreg = *(const u32x4*)(vg + (size_t)(t) * 64 * 512); } while (0)
; __device__ __forceinline__ void attn_unit(LAS unsigned char* lds, const bf16* Q, const bf16* Kp, const bf16* V, bf16* Y, int b, int h, int qb) {
;     ...
;     for (int t = 0; t < NT; ++t) {
;         const int buf = t & 1;
;         if (t + 1 < NT) A_LOAD(t + 1);
.Lat_head1:
	s_add_i32 s25, s13, 2
	s_cmp_lt_u32 s25, s12
	s_cselect_b64 s[50:51], -1, 0
	s_cbranch_scc0 .Lat_noload_1
	global_load_dwordx4 v[142:145], v[154:155], off
	global_load_dwordx4 v[146:149], v[156:157], off
	global_load_dwordx4 v[150:153], v[108:109], off
	s_mov_b64 s[6:7], 0x18000
	v_lshl_add_u64 v[154:155], v[154:155], 0, s[6:7]
	v_lshl_add_u64 v[156:157], v[156:157], 0, s[6:7]
